# pooled-difference slab stores write-through (sc1) as well (whole 1 KB per wave store, consumer on other XCDs); on top of v64
# baseline (speedup 1.0000x reference)
.LBB0_962:
	s_waitcnt lgkmcnt(0)
	s_barrier
	ds_read_b128 v[28:31], v1
	v_lshlrev_b64 v[4:5], 11, v[4:5]
	v_lshl_add_u64 v[4:5], s[6:7], 0, v[4:5]
	v_lshl_add_u64 v[4:5], v[4:5], 0, v[2:3]
	v_add_co_u32_e32 v4, vcc, 0xa400000, v4
	v_lshlrev_b64 v[8:9], 11, v[8:9]
	s_nop 0
	v_addc_co_u32_e32 v5, vcc, 0, v5, vcc
	s_waitcnt lgkmcnt(0)
	global_store_dwordx4 v[4:5], v[28:31], off offset:1024 sc1
	ds_read_b128 v[28:31], v20
	v_lshlrev_b64 v[4:5], 11, v[6:7]
	v_lshl_add_u64 v[4:5], s[6:7], 0, v[4:5]
	v_lshl_add_u64 v[4:5], v[4:5], 0, v[2:3]
	v_add_co_u32_e32 v4, vcc, 0xa400000, v4
	v_lshl_add_u64 v[8:9], s[6:7], 0, v[8:9]
	s_nop 0
	v_addc_co_u32_e32 v5, vcc, 0, v5, vcc
	s_waitcnt lgkmcnt(0)
	global_store_dwordx4 v[4:5], v[28:31], off offset:1024 sc1
	ds_read_b128 v[4:7], v21
	v_lshl_add_u64 v[8:9], v[8:9], 0, v[2:3]
	v_add_co_u32_e32 v8, vcc, 0xa400000, v8
	s_add_i32 s34, s34, s30
	s_nop 0
	v_addc_co_u32_e32 v9, vcc, 0, v9, vcc
	s_waitcnt lgkmcnt(0)
	global_store_dwordx4 v[8:9], v[4:7], off offset:1024 sc1
	ds_read_b128 v[4:7], v22
	v_lshlrev_b64 v[8:9], 11, v[10:11]
	v_lshl_add_u64 v[8:9], s[6:7], 0, v[8:9]
	v_lshl_add_u64 v[8:9], v[8:9], 0, v[2:3]
	v_add_co_u32_e32 v8, vcc, 0xa400000, v8
	s_add_i32 s4, s4, s14
	s_nop 0
	v_addc_co_u32_e32 v9, vcc, 0, v9, vcc
	s_waitcnt lgkmcnt(0)
	global_store_dwordx4 v[8:9], v[4:7], off offset:1024 sc1
	ds_read_b128 v[4:7], v23
	v_lshlrev_b64 v[8:9], 11, v[12:13]
	v_lshl_add_u64 v[8:9], s[6:7], 0, v[8:9]
	v_lshl_add_u64 v[8:9], v[8:9], 0, v[2:3]
	v_add_co_u32_e32 v8, vcc, 0xa400000, v8
	s_cmpk_gt_u32 s34, 0xff
	s_nop 0
	v_addc_co_u32_e32 v9, vcc, 0, v9, vcc
	s_waitcnt lgkmcnt(0)
	global_store_dwordx4 v[8:9], v[4:7], off offset:1024 sc1
	ds_read_b128 v[4:7], v24
	v_lshlrev_b64 v[8:9], 11, v[14:15]
	v_lshl_add_u64 v[8:9], s[6:7], 0, v[8:9]
	v_lshl_add_u64 v[8:9], v[8:9], 0, v[2:3]
	v_add_co_u32_e32 v8, vcc, 0xa400000, v8
	s_nop 1
	v_addc_co_u32_e32 v9, vcc, 0, v9, vcc
	s_waitcnt lgkmcnt(0)
	global_store_dwordx4 v[8:9], v[4:7], off offset:1024 sc1
	ds_read_b128 v[4:7], v25
	v_lshlrev_b64 v[8:9], 11, v[16:17]
	v_lshl_add_u64 v[8:9], s[6:7], 0, v[8:9]
	v_lshl_add_u64 v[8:9], v[8:9], 0, v[2:3]
	v_add_co_u32_e32 v8, vcc, 0xa400000, v8
	s_nop 1
	v_addc_co_u32_e32 v9, vcc, 0, v9, vcc
	s_waitcnt lgkmcnt(0)
	global_store_dwordx4 v[8:9], v[4:7], off offset:1024 sc1
	ds_read_b128 v[4:7], v26
	v_lshlrev_b64 v[8:9], 11, v[18:19]
	v_lshl_add_u64 v[8:9], s[6:7], 0, v[8:9]
	v_lshl_add_u64 v[8:9], v[8:9], 0, v[2:3]
	v_add_co_u32_e32 v8, vcc, 0xa400000, v8
	s_nop 1
	v_addc_co_u32_e32 v9, vcc, 0, v9, vcc
	s_waitcnt lgkmcnt(0)
	global_store_dwordx4 v[8:9], v[4:7], off offset:1024 sc1
	s_cbranch_scc1 .LBB0_977
